# phase0 weight transposes: up to three tiles per iteration with all loads issued together; selection key load without a wait per read
# speedup vs baseline: 1.2269x; 1.0078x over previous
.LBB0_100:
	s_waitcnt lgkmcnt(0)
	s_add_i32 s6, s34, 63
	s_lshr_b32 s39, s6, 6
	s_lshr_b32 s40, s36, 6
	s_mul_i32 s40, s40, s39
	s_cmp_ge_i32 s2, s40
	s_cbranch_scc1 .LBB0_35
	v_cvt_f32_u32_e32 v0, s39
	s_load_dword s24, s[10:11], 0x0
	s_load_dword s25, s[10:11], 0x10
	v_cvt_f32_u32_e32 v1, s38
	s_lshl_b64 s[6:7], s[26:27], 2
	v_rcp_iflag_f32_e32 v0, v0
	s_add_u32 s6, s14, s6
	s_addc_u32 s7, s15, s7
	v_mov_b32_e32 v15, v13
	v_mul_f32_e32 v0, 0x4f7ffffe, v0
	s_cmp_lg_u64 s[12:13], 0
	v_cvt_u32_f32_e32 v0, v0
	v_rcp_iflag_f32_e32 v1, v1
	v_lshl_add_u64 v[16:17], s[6:7], 0, v[14:15]
	s_cselect_b64 s[14:15], -1, 0
	s_waitcnt lgkmcnt(0)
	s_lshr_b32 s6, s25, 16
	s_cmp_lg_u32 s6, 0
	s_cselect_b64 s[6:7], -1, 0
	s_cmp_lg_u64 s[6:7], 0
	v_readfirstlane_b32 s7, v0
	v_mul_f32_e32 v0, 0x4f7ffffe, v1
	s_addc_u32 s41, s24, 0
	s_sub_i32 s6, 0, s39
	v_cvt_u32_f32_e32 v0, v0
	s_mul_i32 s6, s6, s7
	s_mul_hi_u32 s6, s7, s6
	s_add_i32 s42, s7, s6
	s_sub_i32 s6, 0, s38
	v_mul_lo_u32 v1, s6, v0
	v_mul_hi_u32 v1, v0, v1
	s_lshl_b32 s6, s39, 6
	v_add_u32_e32 v15, v0, v1
	s_sub_i32 s43, 0, s6
	s_lshl_b32 s44, s41, 6
	v_cndmask_b32_e64 v21, 0, 1, s[14:15]
	s_mov_b32 s45, s2
	s_mov_b32 s46, s30
	s_branch .LBB0_103
.LBB0_102:
	s_nop 0
.LBB0_103:
	s_mov_b32 s76, 0
	s_mov_b32 s71, s45
	s_cmp_ge_i32 s71, s40
	s_cbranch_scc1 .Lwt_lddone
	s_mov_b32 s76, 1
	s_abs_i32 s7, s71
	s_mul_hi_u32 s24, s7, s42
	s_mul_i32 s25, s24, s39
	s_sub_i32 s7, s7, s25
	s_ashr_i32 s6, s71, 31
	s_add_i32 s25, s24, 1
	s_sub_i32 s26, s7, s39
	s_cmp_ge_u32 s7, s39
	s_cselect_b32 s24, s25, s24
	s_cselect_b32 s7, s26, s7
	s_add_i32 s25, s24, 1
	s_cmp_ge_u32 s7, s39
	s_cselect_b32 s7, s25, s24
	s_xor_b32 s7, s7, s6
	s_sub_i32 s6, s7, s6
	s_lshl_b32 s64, s6, 6
	s_mul_i32 s6, s43, s6
	s_lshl_b32 s72, s71, 6
	s_add_i32 s65, s6, s72
	v_mov_b32_e32 v56, 1.0
	v_mov_b32_e32 v57, 1.0
	v_add_u32_e32 v0, s65, v10
	v_cmp_gt_i32_e32 vcc, s34, v0
	s_and_saveexec_b64 s[28:29], vcc
	s_cbranch_execz .Lwt_skipld0
	s_mov_b32 s26, s65
	v_or_b32_e32 v6, s64, v8
	v_ashrrev_i32_e32 v7, 31, v6
	s_ashr_i32 s27, s26, 31
	v_mul_lo_u32 v2, s16, v7
	v_mul_lo_u32 v3, s17, v6
	v_mad_u64_u32 v[0:1], s[6:7], s16, v6, 0
	v_lshl_add_u64 v[4:5], s[26:27], 2, v[16:17]
	v_add3_u32 v1, v1, v2, v3
	v_lshl_add_u64 v[0:1], v[0:1], 2, v[4:5]
	global_load_dwordx4 v[32:35], v[0:1], off
	s_andn2_b64 vcc, exec, s[14:15]
	s_cbranch_vccnz .Lwt_nog0a
	v_lshl_add_u64 v[6:7], v[6:7], 2, s[12:13]
	global_load_dword v56, v[6:7], off
.Lwt_nog0a:
	v_add_u32_e32 v6, s64, v20
	v_ashrrev_i32_e32 v7, 31, v6
	v_mul_lo_u32 v24, s16, v7
	v_mul_lo_u32 v25, s17, v6
	v_mad_u64_u32 v[6:7], s[48:49], s16, v6, 0
	v_add3_u32 v7, v7, v24, v25
	v_lshl_add_u64 v[4:5], v[6:7], 2, v[4:5]
	global_load_dwordx4 v[36:39], v[4:5], off
	s_andn2_b64 vcc, exec, s[14:15]
	s_cbranch_vccnz .Lwt_nog0b
	s_mov_b32 s24, s64
	s_ashr_i32 s25, s24, 31
	v_lshl_add_u64 v[0:1], s[24:25], 0, v[8:9]
	v_lshl_add_u64 v[0:1], v[0:1], 2, s[12:13]
	global_load_dword v57, v[0:1], off offset:128
.Lwt_nog0b:
.Lwt_skipld0:
	s_or_b64 exec, exec, s[28:29]
	s_add_i32 s71, s71, s41
	s_cmp_ge_i32 s71, s40
	s_cbranch_scc1 .Lwt_lddone
	s_mov_b32 s76, 2
	s_abs_i32 s7, s71
	s_mul_hi_u32 s24, s7, s42
	s_mul_i32 s25, s24, s39
	s_sub_i32 s7, s7, s25
	s_ashr_i32 s6, s71, 31
	s_add_i32 s25, s24, 1
	s_sub_i32 s26, s7, s39
	s_cmp_ge_u32 s7, s39
	s_cselect_b32 s24, s25, s24
	s_cselect_b32 s7, s26, s7
	s_add_i32 s25, s24, 1
	s_cmp_ge_u32 s7, s39
	s_cselect_b32 s7, s25, s24
	s_xor_b32 s7, s7, s6
	s_sub_i32 s6, s7, s6
	s_lshl_b32 s66, s6, 6
	s_mul_i32 s6, s43, s6
	s_lshl_b32 s72, s71, 6
	s_add_i32 s67, s6, s72
	v_mov_b32_e32 v58, 1.0
	v_mov_b32_e32 v59, 1.0
	v_add_u32_e32 v0, s67, v10
	v_cmp_gt_i32_e32 vcc, s34, v0
	s_and_saveexec_b64 s[28:29], vcc
	s_cbranch_execz .Lwt_skipld1
	s_mov_b32 s26, s67
	v_or_b32_e32 v6, s66, v8
	v_ashrrev_i32_e32 v7, 31, v6
	s_ashr_i32 s27, s26, 31
	v_mul_lo_u32 v2, s16, v7
	v_mul_lo_u32 v3, s17, v6
	v_mad_u64_u32 v[0:1], s[6:7], s16, v6, 0
	v_lshl_add_u64 v[4:5], s[26:27], 2, v[16:17]
	v_add3_u32 v1, v1, v2, v3
	v_lshl_add_u64 v[0:1], v[0:1], 2, v[4:5]
	global_load_dwordx4 v[40:43], v[0:1], off
	s_andn2_b64 vcc, exec, s[14:15]
	s_cbranch_vccnz .Lwt_nog1a
	v_lshl_add_u64 v[6:7], v[6:7], 2, s[12:13]
	global_load_dword v58, v[6:7], off
.Lwt_nog1a:
	v_add_u32_e32 v6, s66, v20
	v_ashrrev_i32_e32 v7, 31, v6
	v_mul_lo_u32 v24, s16, v7
	v_mul_lo_u32 v25, s17, v6
	v_mad_u64_u32 v[6:7], s[48:49], s16, v6, 0
	v_add3_u32 v7, v7, v24, v25
	v_lshl_add_u64 v[4:5], v[6:7], 2, v[4:5]
	global_load_dwordx4 v[44:47], v[4:5], off
	s_andn2_b64 vcc, exec, s[14:15]
	s_cbranch_vccnz .Lwt_nog1b
	s_mov_b32 s24, s66
	s_ashr_i32 s25, s24, 31
	v_lshl_add_u64 v[0:1], s[24:25], 0, v[8:9]
	v_lshl_add_u64 v[0:1], v[0:1], 2, s[12:13]
	global_load_dword v59, v[0:1], off offset:128
.Lwt_nog1b:
.Lwt_skipld1:
	s_or_b64 exec, exec, s[28:29]
	s_add_i32 s71, s71, s41
	s_cmp_ge_i32 s71, s40
	s_cbranch_scc1 .Lwt_lddone
	s_mov_b32 s76, 3
	s_abs_i32 s7, s71
	s_mul_hi_u32 s24, s7, s42
	s_mul_i32 s25, s24, s39
	s_sub_i32 s7, s7, s25
	s_ashr_i32 s6, s71, 31
	s_add_i32 s25, s24, 1
	s_sub_i32 s26, s7, s39
	s_cmp_ge_u32 s7, s39
	s_cselect_b32 s24, s25, s24
	s_cselect_b32 s7, s26, s7
	s_add_i32 s25, s24, 1
	s_cmp_ge_u32 s7, s39
	s_cselect_b32 s7, s25, s24
	s_xor_b32 s7, s7, s6
	s_sub_i32 s6, s7, s6
	s_lshl_b32 s68, s6, 6
	s_mul_i32 s6, s43, s6
	s_lshl_b32 s72, s71, 6
	s_add_i32 s69, s6, s72
	v_mov_b32_e32 v60, 1.0
	v_mov_b32_e32 v61, 1.0
	v_add_u32_e32 v0, s69, v10
	v_cmp_gt_i32_e32 vcc, s34, v0
	s_and_saveexec_b64 s[28:29], vcc
	s_cbranch_execz .Lwt_skipld2
	s_mov_b32 s26, s69
	v_or_b32_e32 v6, s68, v8
	v_ashrrev_i32_e32 v7, 31, v6
	s_ashr_i32 s27, s26, 31
	v_mul_lo_u32 v2, s16, v7
	v_mul_lo_u32 v3, s17, v6
	v_mad_u64_u32 v[0:1], s[6:7], s16, v6, 0
	v_lshl_add_u64 v[4:5], s[26:27], 2, v[16:17]
	v_add3_u32 v1, v1, v2, v3
	v_lshl_add_u64 v[0:1], v[0:1], 2, v[4:5]
	global_load_dwordx4 v[48:51], v[0:1], off
	s_andn2_b64 vcc, exec, s[14:15]
	s_cbranch_vccnz .Lwt_nog2a
	v_lshl_add_u64 v[6:7], v[6:7], 2, s[12:13]
	global_load_dword v60, v[6:7], off
.Lwt_nog2a:
	v_add_u32_e32 v6, s68, v20
	v_ashrrev_i32_e32 v7, 31, v6
	v_mul_lo_u32 v24, s16, v7
	v_mul_lo_u32 v25, s17, v6
	v_mad_u64_u32 v[6:7], s[48:49], s16, v6, 0
	v_add3_u32 v7, v7, v24, v25
	v_lshl_add_u64 v[4:5], v[6:7], 2, v[4:5]
	global_load_dwordx4 v[52:55], v[4:5], off
	s_andn2_b64 vcc, exec, s[14:15]
	s_cbranch_vccnz .Lwt_nog2b
	s_mov_b32 s24, s68
	s_ashr_i32 s25, s24, 31
	v_lshl_add_u64 v[0:1], s[24:25], 0, v[8:9]
	v_lshl_add_u64 v[0:1], v[0:1], 2, s[12:13]
	global_load_dword v61, v[0:1], off offset:128
.Lwt_nog2b:
.Lwt_skipld2:
	s_or_b64 exec, exec, s[28:29]
.Lwt_lddone:
	s_waitcnt vmcnt(0)
	s_cmp_lt_u32 s76, 1
	s_cbranch_scc1 .Lwt_cvdone
	v_add_u32_e32 v0, s65, v10
	v_cmp_gt_i32_e32 vcc, s34, v0
	s_and_saveexec_b64 s[28:29], vcc
	s_cbranch_execz .Lwt_skipcv0
	v_mul_f32_e32 v23, s35, v56
	v_mul_f32_e32 v0, v32, v23
	v_cvt_pk_bf16_f32 v0, v0, s0
	ds_write_b16 v19, v0
	v_mul_f32_e32 v0, v33, v23
	v_cvt_pk_bf16_f32 v0, v0, s0
	ds_write_b16 v19, v0 offset:144
	v_mul_f32_e32 v0, v34, v23
	v_cvt_pk_bf16_f32 v0, v0, s0
	ds_write_b16 v19, v0 offset:288
	v_mul_f32_e32 v0, v35, v23
	v_cvt_pk_bf16_f32 v0, v0, s0
	ds_write_b16 v19, v0 offset:432
	v_mul_f32_e32 v0, s35, v57
	v_mul_f32_e32 v1, v36, v0
	v_cvt_pk_bf16_f32 v1, v1, s0
	ds_write_b16 v19, v1 offset:64
	v_mul_f32_e32 v1, v37, v0
	v_cvt_pk_bf16_f32 v1, v1, s0
	ds_write_b16 v19, v1 offset:208
	v_mul_f32_e32 v1, v38, v0
	v_cvt_pk_bf16_f32 v1, v1, s0
	ds_write_b16 v19, v1 offset:352
	v_mul_f32_e32 v1, v39, v0
	v_cvt_pk_bf16_f32 v1, v1, s0
	ds_write_b16 v19, v1 offset:496
.Lwt_skipcv0:
	s_or_b64 exec, exec, s[28:29]
	s_cmp_lt_u32 s76, 2
	s_cbranch_scc1 .Lwt_cvdone
	v_add_u32_e32 v0, s67, v10
	v_cmp_gt_i32_e32 vcc, s34, v0
	s_and_saveexec_b64 s[28:29], vcc
	s_cbranch_execz .Lwt_skipcv1
	v_mul_f32_e32 v23, s35, v58
	v_mul_f32_e32 v0, v40, v23
	v_cvt_pk_bf16_f32 v0, v0, s0
	ds_write_b16 v19, v0 offset:9216
	v_mul_f32_e32 v0, v41, v23
	v_cvt_pk_bf16_f32 v0, v0, s0
	ds_write_b16 v19, v0 offset:9360
	v_mul_f32_e32 v0, v42, v23
	v_cvt_pk_bf16_f32 v0, v0, s0
	ds_write_b16 v19, v0 offset:9504
	v_mul_f32_e32 v0, v43, v23
	v_cvt_pk_bf16_f32 v0, v0, s0
	ds_write_b16 v19, v0 offset:9648
	v_mul_f32_e32 v0, s35, v59
	v_mul_f32_e32 v1, v44, v0
	v_cvt_pk_bf16_f32 v1, v1, s0
	ds_write_b16 v19, v1 offset:9280
	v_mul_f32_e32 v1, v45, v0
	v_cvt_pk_bf16_f32 v1, v1, s0
	ds_write_b16 v19, v1 offset:9424
	v_mul_f32_e32 v1, v46, v0
	v_cvt_pk_bf16_f32 v1, v1, s0
	ds_write_b16 v19, v1 offset:9568
	v_mul_f32_e32 v1, v47, v0
	v_cvt_pk_bf16_f32 v1, v1, s0
	ds_write_b16 v19, v1 offset:9712
.Lwt_skipcv1:
	s_or_b64 exec, exec, s[28:29]
	s_cmp_lt_u32 s76, 3
	s_cbranch_scc1 .Lwt_cvdone
	v_add_u32_e32 v0, s69, v10
	v_cmp_gt_i32_e32 vcc, s34, v0
	s_and_saveexec_b64 s[28:29], vcc
	s_cbranch_execz .Lwt_skipcv2
	v_mul_f32_e32 v23, s35, v60
	v_mul_f32_e32 v0, v48, v23
	v_cvt_pk_bf16_f32 v0, v0, s0
	ds_write_b16 v19, v0 offset:18432
	v_mul_f32_e32 v0, v49, v23
	v_cvt_pk_bf16_f32 v0, v0, s0
	ds_write_b16 v19, v0 offset:18576
	v_mul_f32_e32 v0, v50, v23
	v_cvt_pk_bf16_f32 v0, v0, s0
	ds_write_b16 v19, v0 offset:18720
	v_mul_f32_e32 v0, v51, v23
	v_cvt_pk_bf16_f32 v0, v0, s0
	ds_write_b16 v19, v0 offset:18864
	v_mul_f32_e32 v0, s35, v61
	v_mul_f32_e32 v1, v52, v0
	v_cvt_pk_bf16_f32 v1, v1, s0
	ds_write_b16 v19, v1 offset:18496
	v_mul_f32_e32 v1, v53, v0
	v_cvt_pk_bf16_f32 v1, v1, s0
	ds_write_b16 v19, v1 offset:18640
	v_mul_f32_e32 v1, v54, v0
	v_cvt_pk_bf16_f32 v1, v1, s0
	ds_write_b16 v19, v1 offset:18784
	v_mul_f32_e32 v1, v55, v0
	v_cvt_pk_bf16_f32 v1, v1, s0
	ds_write_b16 v19, v1 offset:18928

.Lwt_cvdone:
	s_waitcnt lgkmcnt(0)
	s_barrier
	s_cmp_lt_u32 s76, 1
	s_cbranch_scc1 .Lwt_stdone
	v_add_u32_e32 v0, s65, v11
	v_cmp_gt_i32_e32 vcc, s34, v0
	s_and_saveexec_b64 s[6:7], vcc
	s_cbranch_execz .Lwt_skipst0
	s_mov_b32 s24, s64
	v_sub_u32_e32 v2, 0, v0
	v_max_i32_e32 v2, v0, v2
	v_mul_hi_u32 v3, v2, v15
	v_mul_lo_u32 v4, v3, s38
	v_sub_u32_e32 v2, v2, v4
	v_add_u32_e32 v4, 1, v3
	v_cmp_le_u32_e32 vcc, s38, v2
	v_ashrrev_i32_e32 v1, 31, v0
	s_ashr_i32 s25, s24, 31
	v_cndmask_b32_e32 v3, v3, v4, vcc
	v_subrev_u32_e32 v4, s38, v2
	v_cndmask_b32_e32 v2, v2, v4, vcc
	v_add_u32_e32 v4, 1, v3
	v_cmp_le_u32_e32 vcc, s38, v2
	s_nop 1
	v_cndmask_b32_e32 v2, v3, v4, vcc
	v_xor_b32_e32 v2, v2, v1
	v_sub_u32_e32 v1, v2, v1
	v_mul_lo_u32 v2, v1, s37
	v_mul_lo_u32 v1, v1, s38
	v_sub_u32_e32 v0, v0, v1
	v_add3_u32 v4, v2, s31, v0
	v_ashrrev_i32_e32 v7, 31, v4
	v_mad_u64_u32 v[4:5], s[26:27], v4, s36, 0
	v_mov_b32_e32 v6, v5
	ds_read_b128 v[0:3], v18
	v_mad_u64_u32 v[6:7], s[26:27], v7, s36, v[6:7]
	v_mov_b32_e32 v5, v6
	v_lshl_add_u64 v[4:5], v[4:5], 1, s[8:9]
	v_lshl_add_u64 v[4:5], s[24:25], 1, v[4:5]
	v_lshl_add_u64 v[4:5], v[4:5], 0, v[12:13]
	s_waitcnt lgkmcnt(0)
	global_store_dwordx4 v[4:5], v[0:3], off
.Lwt_skipst0:
	s_or_b64 exec, exec, s[6:7]
	s_cmp_lt_u32 s76, 2
	s_cbranch_scc1 .Lwt_stdone
	v_add_u32_e32 v0, s67, v11
	v_cmp_gt_i32_e32 vcc, s34, v0
	s_and_saveexec_b64 s[6:7], vcc
	s_cbranch_execz .Lwt_skipst1
	s_mov_b32 s24, s66
	v_sub_u32_e32 v2, 0, v0
	v_max_i32_e32 v2, v0, v2
	v_mul_hi_u32 v3, v2, v15
	v_mul_lo_u32 v4, v3, s38
	v_sub_u32_e32 v2, v2, v4
	v_add_u32_e32 v4, 1, v3
	v_cmp_le_u32_e32 vcc, s38, v2
	v_ashrrev_i32_e32 v1, 31, v0
	s_ashr_i32 s25, s24, 31
	v_cndmask_b32_e32 v3, v3, v4, vcc
	v_subrev_u32_e32 v4, s38, v2
	v_cndmask_b32_e32 v2, v2, v4, vcc
	v_add_u32_e32 v4, 1, v3
	v_cmp_le_u32_e32 vcc, s38, v2
	s_nop 1
	v_cndmask_b32_e32 v2, v3, v4, vcc
	v_xor_b32_e32 v2, v2, v1
	v_sub_u32_e32 v1, v2, v1
	v_mul_lo_u32 v2, v1, s37
	v_mul_lo_u32 v1, v1, s38
	v_sub_u32_e32 v0, v0, v1
	v_add3_u32 v4, v2, s31, v0
	v_ashrrev_i32_e32 v7, 31, v4
	v_mad_u64_u32 v[4:5], s[26:27], v4, s36, 0
	v_mov_b32_e32 v6, v5
	ds_read_b128 v[0:3], v18 offset:9216
	v_mad_u64_u32 v[6:7], s[26:27], v7, s36, v[6:7]
	v_mov_b32_e32 v5, v6
	v_lshl_add_u64 v[4:5], v[4:5], 1, s[8:9]
	v_lshl_add_u64 v[4:5], s[24:25], 1, v[4:5]
	v_lshl_add_u64 v[4:5], v[4:5], 0, v[12:13]
	s_waitcnt lgkmcnt(0)
	global_store_dwordx4 v[4:5], v[0:3], off
.Lwt_skipst1:
	s_or_b64 exec, exec, s[6:7]
	s_cmp_lt_u32 s76, 3
	s_cbranch_scc1 .Lwt_stdone
	v_add_u32_e32 v0, s69, v11
	v_cmp_gt_i32_e32 vcc, s34, v0
	s_and_saveexec_b64 s[6:7], vcc
	s_cbranch_execz .Lwt_skipst2
	s_mov_b32 s24, s68
	v_sub_u32_e32 v2, 0, v0
	v_max_i32_e32 v2, v0, v2
	v_mul_hi_u32 v3, v2, v15
	v_mul_lo_u32 v4, v3, s38
	v_sub_u32_e32 v2, v2, v4
	v_add_u32_e32 v4, 1, v3
	v_cmp_le_u32_e32 vcc, s38, v2
	v_ashrrev_i32_e32 v1, 31, v0
	s_ashr_i32 s25, s24, 31
	v_cndmask_b32_e32 v3, v3, v4, vcc
	v_subrev_u32_e32 v4, s38, v2
	v_cndmask_b32_e32 v2, v2, v4, vcc
	v_add_u32_e32 v4, 1, v3
	v_cmp_le_u32_e32 vcc, s38, v2
	s_nop 1
	v_cndmask_b32_e32 v2, v3, v4, vcc
	v_xor_b32_e32 v2, v2, v1
	v_sub_u32_e32 v1, v2, v1
	v_mul_lo_u32 v2, v1, s37
	v_mul_lo_u32 v1, v1, s38
	v_sub_u32_e32 v0, v0, v1
	v_add3_u32 v4, v2, s31, v0
	v_ashrrev_i32_e32 v7, 31, v4
	v_mad_u64_u32 v[4:5], s[26:27], v4, s36, 0
	v_mov_b32_e32 v6, v5
	ds_read_b128 v[0:3], v18 offset:18432
	v_mad_u64_u32 v[6:7], s[26:27], v7, s36, v[6:7]
	v_mov_b32_e32 v5, v6
	v_lshl_add_u64 v[4:5], v[4:5], 1, s[8:9]
	v_lshl_add_u64 v[4:5], s[24:25], 1, v[4:5]
	v_lshl_add_u64 v[4:5], v[4:5], 0, v[12:13]
	s_waitcnt lgkmcnt(0)
	global_store_dwordx4 v[4:5], v[0:3], off

.Lwt_stdone:
	s_mul_i32 s70, s41, 3
	s_add_i32 s45, s45, s70
	s_cmp_ge_i32 s45, s40
	s_barrier
	s_cbranch_scc1 .LBB0_35
	s_branch .LBB0_103

.LBB0_1644:
	s_andn2_b64 vcc, exec, s[6:7]
	s_cbranch_vccnz .LBB0_1713
	s_add_i32 s54, s54, s14
	s_cmpk_gt_i32 s54, 0xff
	s_cbranch_scc0 .LBB0_1714
	s_and_b32 s12, s8, -16
	s_mov_b32 s6, s12
	v_mov_b32_e32 v63, 0
	s_cmp_lt_i32 s6, 1
	v_mov_b32_e32 v64, 0
	s_cbranch_scc1 .LBB0_1648
	ds_read_b32 v64, v190
.LBB0_1648:
	s_cmpk_lt_i32 s6, 0x41
	s_cbranch_scc1 .LBB0_1715
	ds_read_b32 v63, v190 offset:256
	v_mov_b32_e32 v61, 0
	s_cmpk_lt_i32 s6, 0x81
	v_mov_b32_e32 v62, 0
	s_cbranch_scc0 .LBB0_1716

.LBB0_1651:
	ds_read_b32 v61, v190 offset:768
	v_mov_b32_e32 v59, 0
	s_cmpk_lt_i32 s6, 0x101
	v_mov_b32_e32 v60, 0
	s_cbranch_scc0 .LBB0_1718

.LBB0_1653:
	ds_read_b32 v59, v190 offset:1280
	v_mov_b32_e32 v57, 0
	s_cmpk_lt_i32 s6, 0x181
	v_mov_b32_e32 v58, 0
	s_cbranch_scc0 .LBB0_1720

.LBB0_1655:
	ds_read_b32 v57, v190 offset:1792
	v_mov_b32_e32 v55, 0
	s_cmpk_lt_i32 s6, 0x201
	v_mov_b32_e32 v56, 0
	s_cbranch_scc0 .LBB0_1722

.LBB0_1657:
	ds_read_b32 v55, v190 offset:2304
	v_mov_b32_e32 v53, 0
	s_cmpk_lt_i32 s6, 0x281
	v_mov_b32_e32 v54, 0
	s_cbranch_scc0 .LBB0_1724

.LBB0_1659:
	ds_read_b32 v53, v190 offset:2816
	v_mov_b32_e32 v51, 0
	s_cmpk_lt_i32 s6, 0x301
	v_mov_b32_e32 v52, 0
	s_cbranch_scc0 .LBB0_1726

.LBB0_1661:
	ds_read_b32 v51, v190 offset:3328
	v_mov_b32_e32 v49, 0
	s_cmpk_lt_i32 s6, 0x381
	v_mov_b32_e32 v50, 0
	s_cbranch_scc0 .LBB0_1728

.LBB0_1665:
	ds_read_b32 v47, v190 offset:4352
	v_mov_b32_e32 v45, 0
	s_cmpk_lt_i32 s6, 0x481
	v_mov_b32_e32 v46, 0
	s_cbranch_scc0 .LBB0_1732

.LBB0_1667:
	ds_read_b32 v45, v190 offset:4864
	v_mov_b32_e32 v43, 0
	s_cmpk_lt_i32 s6, 0x501
	v_mov_b32_e32 v44, 0
	s_cbranch_scc0 .LBB0_1734

.LBB0_1669:
	ds_read_b32 v43, v190 offset:5376
	v_mov_b32_e32 v41, 0
	s_cmpk_lt_i32 s6, 0x581
	v_mov_b32_e32 v42, 0
	s_cbranch_scc0 .LBB0_1736

.LBB0_1671:
	ds_read_b32 v41, v190 offset:5888
	v_mov_b32_e32 v39, 0
	s_cmpk_lt_i32 s6, 0x601
	v_mov_b32_e32 v40, 0
	s_cbranch_scc0 .LBB0_1738

.LBB0_1673:
	ds_read_b32 v39, v190 offset:6400
	v_mov_b32_e32 v37, 0
	s_cmpk_lt_i32 s6, 0x681
	v_mov_b32_e32 v38, 0
	s_cbranch_scc0 .LBB0_1740

.LBB0_1675:
	ds_read_b32 v37, v190 offset:6912
	v_mov_b32_e32 v35, 0
	s_cmpk_lt_i32 s6, 0x701
	v_mov_b32_e32 v36, 0
	s_cbranch_scc0 .LBB0_1742

.LBB0_1677:
	ds_read_b32 v35, v190 offset:7424
	v_mov_b32_e32 v33, 0
	s_cmpk_lt_i32 s6, 0x781
	v_mov_b32_e32 v34, 0
	s_cbranch_scc0 .LBB0_1744

.LBB0_1681:
	ds_read_b32 v31, v190 offset:8448
	v_mov_b32_e32 v29, 0
	s_cmpk_lt_i32 s6, 0x881
	v_mov_b32_e32 v30, 0
	s_cbranch_scc0 .LBB0_1748

.LBB0_1683:
	ds_read_b32 v29, v190 offset:8960
	v_mov_b32_e32 v27, 0
	s_cmpk_lt_i32 s6, 0x901
	v_mov_b32_e32 v28, 0
	s_cbranch_scc0 .LBB0_1750

.LBB0_1685:
	ds_read_b32 v27, v190 offset:9472
	v_mov_b32_e32 v25, 0
	s_cmpk_lt_i32 s6, 0x981
	v_mov_b32_e32 v26, 0
	s_cbranch_scc0 .LBB0_1752

.LBB0_1687:
	ds_read_b32 v25, v190 offset:9984
	v_mov_b32_e32 v23, 0
	s_cmpk_lt_i32 s6, 0xa01
	v_mov_b32_e32 v24, 0
	s_cbranch_scc0 .LBB0_1754

.LBB0_1689:
	ds_read_b32 v23, v190 offset:10496
	v_mov_b32_e32 v21, 0
	s_cmpk_lt_i32 s6, 0xa81
	v_mov_b32_e32 v22, 0
	s_cbranch_scc0 .LBB0_1756

.LBB0_1691:
	ds_read_b32 v21, v190 offset:11008
	v_mov_b32_e32 v19, 0
	s_cmpk_lt_i32 s6, 0xb01
	v_mov_b32_e32 v20, 0
	s_cbranch_scc0 .LBB0_1758

.LBB0_1693:
	ds_read_b32 v19, v190 offset:11520
	v_mov_b32_e32 v17, 0
	s_cmpk_lt_i32 s6, 0xb81
	v_mov_b32_e32 v18, 0
	s_cbranch_scc0 .LBB0_1760

.LBB0_1697:
	ds_read_b32 v15, v190 offset:12544
	v_mov_b32_e32 v13, 0
	s_cmpk_lt_i32 s6, 0xc81
	v_mov_b32_e32 v14, 0
	s_cbranch_scc0 .LBB0_1764

.LBB0_1699:
	ds_read_b32 v13, v190 offset:13056
	v_mov_b32_e32 v11, 0
	s_cmpk_lt_i32 s6, 0xd01
	v_mov_b32_e32 v12, 0
	s_cbranch_scc0 .LBB0_1766

.LBB0_1701:
	ds_read_b32 v11, v190 offset:13568
	v_mov_b32_e32 v9, 0
	s_cmpk_lt_i32 s6, 0xd81
	v_mov_b32_e32 v10, 0
	s_cbranch_scc0 .LBB0_1768

.LBB0_1703:
	ds_read_b32 v9, v190 offset:14080
	v_mov_b32_e32 v7, 0
	s_cmpk_lt_i32 s6, 0xe01
	v_mov_b32_e32 v8, 0
	s_cbranch_scc0 .LBB0_1770

.LBB0_1705:
	ds_read_b32 v7, v190 offset:14592
	v_mov_b32_e32 v5, 0
	s_cmpk_lt_i32 s6, 0xe81
	v_mov_b32_e32 v6, 0
	s_cbranch_scc0 .LBB0_1772

.LBB0_1707:
	ds_read_b32 v5, v190 offset:15104
	v_mov_b32_e32 v3, 0
	s_cmpk_lt_i32 s6, 0xf01
	v_mov_b32_e32 v4, 0
	s_cbranch_scc0 .LBB0_1774

.LBB0_1709:
	ds_read_b32 v3, v190 offset:15616
	v_mov_b32_e32 v0, 0
	s_cmpk_lt_i32 s6, 0xf81
	v_mov_b32_e32 v2, 0
	s_cbranch_scc0 .LBB0_1776

.LBB0_1711:
	v_lshl_add_u32 v0, v211, 2, s3
	ds_read_b32 v0, v0
	v_cmp_gt_i32_e32 vcc, s6, v211
	s_waitcnt lgkmcnt(0)
	s_nop 0
	v_cndmask_b32_e32 v0, 0, v0, vcc
	s_waitcnt lgkmcnt(0)
	v_cmp_gt_i32_e64 s[90:91], s6, v186
	s_sub_i32 s97, s6, 64
	v_cmp_gt_i32_e64 s[92:93], s97, v186
	s_sub_i32 s98, s6, 0xc0
	v_cmp_gt_i32_e64 s[94:95], s98, v186
	v_cndmask_b32_e64 v64, 0, v64, s[90:91]
	s_sub_i32 s96, s6, 0x140
	v_cmp_gt_i32_e64 s[90:91], s96, v186
	v_cndmask_b32_e64 v63, 0, v63, s[92:93]
	s_sub_i32 s97, s6, 0x1c0
	v_cmp_gt_i32_e64 s[92:93], s97, v186
	v_cndmask_b32_e64 v61, 0, v61, s[94:95]
	s_sub_i32 s98, s6, 0x240
	v_cmp_gt_i32_e64 s[94:95], s98, v186
	v_cndmask_b32_e64 v59, 0, v59, s[90:91]
	s_sub_i32 s96, s6, 0x2c0
	v_cmp_gt_i32_e64 s[90:91], s96, v186
	v_cndmask_b32_e64 v57, 0, v57, s[92:93]
	s_sub_i32 s97, s6, 0x340
	v_cmp_gt_i32_e64 s[92:93], s97, v186
	v_cndmask_b32_e64 v55, 0, v55, s[94:95]
	s_sub_i32 s98, s6, 0x440
	v_cmp_gt_i32_e64 s[94:95], s98, v186
	v_cndmask_b32_e64 v53, 0, v53, s[90:91]
	s_sub_i32 s96, s6, 0x4c0
	v_cmp_gt_i32_e64 s[90:91], s96, v186
	v_cndmask_b32_e64 v51, 0, v51, s[92:93]
	s_sub_i32 s97, s6, 0x540
	v_cmp_gt_i32_e64 s[92:93], s97, v186
	v_cndmask_b32_e64 v47, 0, v47, s[94:95]
	s_sub_i32 s98, s6, 0x5c0
	v_cmp_gt_i32_e64 s[94:95], s98, v186
	v_cndmask_b32_e64 v45, 0, v45, s[90:91]
	s_sub_i32 s96, s6, 0x640
	v_cmp_gt_i32_e64 s[90:91], s96, v186
	v_cndmask_b32_e64 v43, 0, v43, s[92:93]
	s_sub_i32 s97, s6, 0x6c0
	v_cmp_gt_i32_e64 s[92:93], s97, v186
	v_cndmask_b32_e64 v41, 0, v41, s[94:95]
	s_sub_i32 s98, s6, 0x740
	v_cmp_gt_i32_e64 s[94:95], s98, v186
	v_cndmask_b32_e64 v39, 0, v39, s[90:91]
	s_sub_i32 s96, s6, 0x840
	v_cmp_gt_i32_e64 s[90:91], s96, v186
	v_cndmask_b32_e64 v37, 0, v37, s[92:93]
	s_sub_i32 s97, s6, 0x8c0
	v_cmp_gt_i32_e64 s[92:93], s97, v186
	v_cndmask_b32_e64 v35, 0, v35, s[94:95]
	s_sub_i32 s98, s6, 0x940
	v_cmp_gt_i32_e64 s[94:95], s98, v186
	v_cndmask_b32_e64 v31, 0, v31, s[90:91]
	s_sub_i32 s96, s6, 0x9c0
	v_cmp_gt_i32_e64 s[90:91], s96, v186
	v_cndmask_b32_e64 v29, 0, v29, s[92:93]
	s_sub_i32 s97, s6, 0xa40
	v_cmp_gt_i32_e64 s[92:93], s97, v186
	v_cndmask_b32_e64 v27, 0, v27, s[94:95]
	s_sub_i32 s98, s6, 0xac0
	v_cmp_gt_i32_e64 s[94:95], s98, v186
	v_cndmask_b32_e64 v25, 0, v25, s[90:91]
	s_sub_i32 s96, s6, 0xb40
	v_cmp_gt_i32_e64 s[90:91], s96, v186
	v_cndmask_b32_e64 v23, 0, v23, s[92:93]
	s_sub_i32 s97, s6, 0xc40
	v_cmp_gt_i32_e64 s[92:93], s97, v186
	v_cndmask_b32_e64 v21, 0, v21, s[94:95]
	s_sub_i32 s98, s6, 0xcc0
	v_cmp_gt_i32_e64 s[94:95], s98, v186
	v_cndmask_b32_e64 v19, 0, v19, s[90:91]
	s_sub_i32 s96, s6, 0xd40
	v_cmp_gt_i32_e64 s[90:91], s96, v186
	v_cndmask_b32_e64 v15, 0, v15, s[92:93]
	s_sub_i32 s97, s6, 0xdc0
	v_cmp_gt_i32_e64 s[92:93], s97, v186
	v_cndmask_b32_e64 v13, 0, v13, s[94:95]
	s_sub_i32 s98, s6, 0xe40
	v_cmp_gt_i32_e64 s[94:95], s98, v186
	v_cndmask_b32_e64 v11, 0, v11, s[90:91]
	s_sub_i32 s96, s6, 0xec0
	v_cmp_gt_i32_e64 s[90:91], s96, v186
	v_cndmask_b32_e64 v9, 0, v9, s[92:93]
	s_sub_i32 s97, s6, 0xf40
	v_cmp_gt_i32_e64 s[92:93], s97, v186
	v_cndmask_b32_e64 v7, 0, v7, s[94:95]
	s_sub_i32 s98, s6, 0x80
	v_cmp_gt_i32_e64 s[94:95], s98, v186
	v_cndmask_b32_e64 v5, 0, v5, s[90:91]
	s_sub_i32 s96, s6, 0x100
	v_cmp_gt_i32_e64 s[90:91], s96, v186
	v_cndmask_b32_e64 v3, 0, v3, s[92:93]
	s_sub_i32 s97, s6, 0x180
	v_cmp_gt_i32_e64 s[92:93], s97, v186
	v_cndmask_b32_e64 v62, 0, v62, s[94:95]
	s_sub_i32 s98, s6, 0x200
	v_cmp_gt_i32_e64 s[94:95], s98, v186
	v_cndmask_b32_e64 v60, 0, v60, s[90:91]
	s_sub_i32 s96, s6, 0x280
	v_cmp_gt_i32_e64 s[90:91], s96, v186
	v_cndmask_b32_e64 v58, 0, v58, s[92:93]
	s_sub_i32 s97, s6, 0x300
	v_cmp_gt_i32_e64 s[92:93], s97, v186
	v_cndmask_b32_e64 v56, 0, v56, s[94:95]
	s_sub_i32 s98, s6, 0x380
	v_cmp_gt_i32_e64 s[94:95], s98, v186
	v_cndmask_b32_e64 v54, 0, v54, s[90:91]
	s_sub_i32 s96, s6, 0x400
	v_cmp_gt_i32_e64 s[90:91], s96, v186
	v_cndmask_b32_e64 v52, 0, v52, s[92:93]
	s_sub_i32 s97, s6, 0x480
	v_cmp_gt_i32_e64 s[92:93], s97, v186
	v_cndmask_b32_e64 v50, 0, v50, s[94:95]
	s_sub_i32 s98, s6, 0x500
	v_cmp_gt_i32_e64 s[94:95], s98, v186
	v_cndmask_b32_e64 v48, 0, v48, s[90:91]
	s_sub_i32 s96, s6, 0x580
	v_cmp_gt_i32_e64 s[90:91], s96, v186
	v_cndmask_b32_e64 v46, 0, v46, s[92:93]
	s_sub_i32 s97, s6, 0x600
	v_cmp_gt_i32_e64 s[92:93], s97, v186
	v_cndmask_b32_e64 v44, 0, v44, s[94:95]
	s_sub_i32 s98, s6, 0x680
	v_cmp_gt_i32_e64 s[94:95], s98, v186
	v_cndmask_b32_e64 v42, 0, v42, s[90:91]
	s_sub_i32 s96, s6, 0x700
	v_cmp_gt_i32_e64 s[90:91], s96, v186
	v_cndmask_b32_e64 v40, 0, v40, s[92:93]
	s_sub_i32 s97, s6, 0x780
	v_cmp_gt_i32_e64 s[92:93], s97, v186
	v_cndmask_b32_e64 v38, 0, v38, s[94:95]
	s_sub_i32 s98, s6, 0x800
	v_cmp_gt_i32_e64 s[94:95], s98, v186
	v_cndmask_b32_e64 v36, 0, v36, s[90:91]
	s_sub_i32 s96, s6, 0x880
	v_cmp_gt_i32_e64 s[90:91], s96, v186
	v_cndmask_b32_e64 v34, 0, v34, s[92:93]
	s_sub_i32 s97, s6, 0x900
	v_cmp_gt_i32_e64 s[92:93], s97, v186
	v_cndmask_b32_e64 v32, 0, v32, s[94:95]
	s_sub_i32 s98, s6, 0x980
	v_cmp_gt_i32_e64 s[94:95], s98, v186
	v_cndmask_b32_e64 v30, 0, v30, s[90:91]
	s_sub_i32 s96, s6, 0xa00
	v_cmp_gt_i32_e64 s[90:91], s96, v186
	v_cndmask_b32_e64 v28, 0, v28, s[92:93]
	s_sub_i32 s97, s6, 0xa80
	v_cmp_gt_i32_e64 s[92:93], s97, v186
	v_cndmask_b32_e64 v26, 0, v26, s[94:95]
	s_sub_i32 s98, s6, 0xb00
	v_cmp_gt_i32_e64 s[94:95], s98, v186
	v_cndmask_b32_e64 v24, 0, v24, s[90:91]
	s_sub_i32 s96, s6, 0xb80
	v_cmp_gt_i32_e64 s[90:91], s96, v186
	v_cndmask_b32_e64 v22, 0, v22, s[92:93]
	s_sub_i32 s97, s6, 0xc00
	v_cmp_gt_i32_e64 s[92:93], s97, v186
	v_cndmask_b32_e64 v20, 0, v20, s[94:95]
	s_sub_i32 s98, s6, 0xc80
	v_cmp_gt_i32_e64 s[94:95], s98, v186
	v_cndmask_b32_e64 v18, 0, v18, s[90:91]
	s_sub_i32 s96, s6, 0xd00
	v_cmp_gt_i32_e64 s[90:91], s96, v186
	v_cndmask_b32_e64 v16, 0, v16, s[92:93]
	s_sub_i32 s97, s6, 0xd80
	v_cmp_gt_i32_e64 s[92:93], s97, v186
	v_cndmask_b32_e64 v14, 0, v14, s[94:95]
	s_sub_i32 s98, s6, 0xe00
	v_cmp_gt_i32_e64 s[94:95], s98, v186
	v_cndmask_b32_e64 v12, 0, v12, s[90:91]
	s_sub_i32 s96, s6, 0xe80
	v_cmp_gt_i32_e64 s[90:91], s96, v186
	v_cndmask_b32_e64 v10, 0, v10, s[92:93]
	s_sub_i32 s97, s6, 0xf00
	v_cmp_gt_i32_e64 s[92:93], s97, v186
	v_cndmask_b32_e64 v8, 0, v8, s[94:95]
	v_cndmask_b32_e64 v6, 0, v6, s[90:91]
	v_cndmask_b32_e64 v4, 0, v4, s[92:93]
	s_add_i32 s6, s12, 63
	s_ashr_i32 s10, s6, 6
	s_cmpk_gt_i32 s12, 0x400
	s_cbranch_scc1 .LBB0_1778

.LBB0_1716:
	ds_read_b32 v62, v190 offset:512
	s_cmpk_lt_i32 s6, 0xc1
	s_cbranch_scc0 .LBB0_1651

.LBB0_1718:
	ds_read_b32 v60, v190 offset:1024
	s_cmpk_lt_i32 s6, 0x141
	s_cbranch_scc0 .LBB0_1653

.LBB0_1720:
	ds_read_b32 v58, v190 offset:1536
	s_cmpk_lt_i32 s6, 0x1c1
	s_cbranch_scc0 .LBB0_1655

.LBB0_1722:
	ds_read_b32 v56, v190 offset:2048
	s_cmpk_lt_i32 s6, 0x241
	s_cbranch_scc0 .LBB0_1657

.LBB0_1724:
	ds_read_b32 v54, v190 offset:2560
	s_cmpk_lt_i32 s6, 0x2c1
	s_cbranch_scc0 .LBB0_1659

.LBB0_1726:
	ds_read_b32 v52, v190 offset:3072
	s_cmpk_lt_i32 s6, 0x341
	s_cbranch_scc0 .LBB0_1661

.LBB0_1728:
	ds_read_b32 v50, v190 offset:3584
	s_cmpk_lt_i32 s6, 0x3c1
	s_cbranch_scc0 .LBB0_1663

.LBB0_1730:
	ds_read_b32 v48, v190 offset:4096
	s_cmpk_lt_i32 s6, 0x441
	s_cbranch_scc0 .LBB0_1665

.LBB0_1732:
	ds_read_b32 v46, v190 offset:4608
	s_cmpk_lt_i32 s6, 0x4c1
	s_cbranch_scc0 .LBB0_1667

.LBB0_1734:
	ds_read_b32 v44, v190 offset:5120
	s_cmpk_lt_i32 s6, 0x541
	s_cbranch_scc0 .LBB0_1669

.LBB0_1736:
	ds_read_b32 v42, v190 offset:5632
	s_cmpk_lt_i32 s6, 0x5c1
	s_cbranch_scc0 .LBB0_1671

.LBB0_1738:
	ds_read_b32 v40, v190 offset:6144
	s_cmpk_lt_i32 s6, 0x641
	s_cbranch_scc0 .LBB0_1673

.LBB0_1740:
	ds_read_b32 v38, v190 offset:6656
	s_cmpk_lt_i32 s6, 0x6c1
	s_cbranch_scc0 .LBB0_1675

.LBB0_1742:
	ds_read_b32 v36, v190 offset:7168
	s_cmpk_lt_i32 s6, 0x741
	s_cbranch_scc0 .LBB0_1677

.LBB0_1744:
	ds_read_b32 v34, v190 offset:7680
	s_cmpk_lt_i32 s6, 0x7c1
	s_cbranch_scc0 .LBB0_1679

.LBB0_1746:
	ds_read_b32 v32, v190 offset:8192
	s_cmpk_lt_i32 s6, 0x841
	s_cbranch_scc0 .LBB0_1681

.LBB0_1748:
	ds_read_b32 v30, v190 offset:8704
	s_cmpk_lt_i32 s6, 0x8c1
	s_cbranch_scc0 .LBB0_1683

.LBB0_1750:
	ds_read_b32 v28, v190 offset:9216
	s_cmpk_lt_i32 s6, 0x941
	s_cbranch_scc0 .LBB0_1685

.LBB0_1752:
	ds_read_b32 v26, v190 offset:9728
	s_cmpk_lt_i32 s6, 0x9c1
	s_cbranch_scc0 .LBB0_1687

.LBB0_1754:
	ds_read_b32 v24, v190 offset:10240
	s_cmpk_lt_i32 s6, 0xa41
	s_cbranch_scc0 .LBB0_1689

.LBB0_1756:
	ds_read_b32 v22, v190 offset:10752
	s_cmpk_lt_i32 s6, 0xac1
	s_cbranch_scc0 .LBB0_1691

.LBB0_1758:
	ds_read_b32 v20, v190 offset:11264
	s_cmpk_lt_i32 s6, 0xb41
	s_cbranch_scc0 .LBB0_1693

.LBB0_1760:
	ds_read_b32 v18, v190 offset:11776
	s_cmpk_lt_i32 s6, 0xbc1
	s_cbranch_scc0 .LBB0_1695

.LBB0_1762:
	ds_read_b32 v16, v190 offset:12288
	s_cmpk_lt_i32 s6, 0xc41
	s_cbranch_scc0 .LBB0_1697

.LBB0_1764:
	ds_read_b32 v14, v190 offset:12800
	s_cmpk_lt_i32 s6, 0xcc1
	s_cbranch_scc0 .LBB0_1699

.LBB0_1766:
	ds_read_b32 v12, v190 offset:13312
	s_cmpk_lt_i32 s6, 0xd41
	s_cbranch_scc0 .LBB0_1701

.LBB0_1768:
	ds_read_b32 v10, v190 offset:13824
	s_cmpk_lt_i32 s6, 0xdc1
	s_cbranch_scc0 .LBB0_1703

.LBB0_1770:
	ds_read_b32 v8, v190 offset:14336
	s_cmpk_lt_i32 s6, 0xe41
	s_cbranch_scc0 .LBB0_1705

.LBB0_1772:
	ds_read_b32 v6, v190 offset:14848
	s_cmpk_lt_i32 s6, 0xec1
	s_cbranch_scc0 .LBB0_1707

.LBB0_1774:
	ds_read_b32 v4, v190 offset:15360
	s_cmpk_lt_i32 s6, 0xf41
	s_cbranch_scc0 .LBB0_1709

.LBB0_1777:
	s_waitcnt lgkmcnt(0)
	v_cmp_gt_i32_e64 s[90:91], s6, v186
	s_sub_i32 s97, s6, 64
	v_cmp_gt_i32_e64 s[92:93], s97, v186
	s_sub_i32 s98, s6, 0xc0
	v_cmp_gt_i32_e64 s[94:95], s98, v186
	v_cndmask_b32_e64 v64, 0, v64, s[90:91]
	s_sub_i32 s96, s6, 0x140
	v_cmp_gt_i32_e64 s[90:91], s96, v186
	v_cndmask_b32_e64 v63, 0, v63, s[92:93]
	s_sub_i32 s97, s6, 0x1c0
	v_cmp_gt_i32_e64 s[92:93], s97, v186
	v_cndmask_b32_e64 v61, 0, v61, s[94:95]
	s_sub_i32 s98, s6, 0x240
	v_cmp_gt_i32_e64 s[94:95], s98, v186
	v_cndmask_b32_e64 v59, 0, v59, s[90:91]
	s_sub_i32 s96, s6, 0x2c0
	v_cmp_gt_i32_e64 s[90:91], s96, v186
	v_cndmask_b32_e64 v57, 0, v57, s[92:93]
	s_sub_i32 s97, s6, 0x340
	v_cmp_gt_i32_e64 s[92:93], s97, v186
	v_cndmask_b32_e64 v55, 0, v55, s[94:95]
	s_sub_i32 s98, s6, 0x440
	v_cmp_gt_i32_e64 s[94:95], s98, v186
	v_cndmask_b32_e64 v53, 0, v53, s[90:91]
	s_sub_i32 s96, s6, 0x4c0
	v_cmp_gt_i32_e64 s[90:91], s96, v186
	v_cndmask_b32_e64 v51, 0, v51, s[92:93]
	s_sub_i32 s97, s6, 0x540
	v_cmp_gt_i32_e64 s[92:93], s97, v186
	v_cndmask_b32_e64 v47, 0, v47, s[94:95]
	s_sub_i32 s98, s6, 0x5c0
	v_cmp_gt_i32_e64 s[94:95], s98, v186
	v_cndmask_b32_e64 v45, 0, v45, s[90:91]
	s_sub_i32 s96, s6, 0x640
	v_cmp_gt_i32_e64 s[90:91], s96, v186
	v_cndmask_b32_e64 v43, 0, v43, s[92:93]
	s_sub_i32 s97, s6, 0x6c0
	v_cmp_gt_i32_e64 s[92:93], s97, v186
	v_cndmask_b32_e64 v41, 0, v41, s[94:95]
	s_sub_i32 s98, s6, 0x740
	v_cmp_gt_i32_e64 s[94:95], s98, v186
	v_cndmask_b32_e64 v39, 0, v39, s[90:91]
	s_sub_i32 s96, s6, 0x840
	v_cmp_gt_i32_e64 s[90:91], s96, v186
	v_cndmask_b32_e64 v37, 0, v37, s[92:93]
	s_sub_i32 s97, s6, 0x8c0
	v_cmp_gt_i32_e64 s[92:93], s97, v186
	v_cndmask_b32_e64 v35, 0, v35, s[94:95]
	s_sub_i32 s98, s6, 0x940
	v_cmp_gt_i32_e64 s[94:95], s98, v186
	v_cndmask_b32_e64 v31, 0, v31, s[90:91]
	s_sub_i32 s96, s6, 0x9c0
	v_cmp_gt_i32_e64 s[90:91], s96, v186
	v_cndmask_b32_e64 v29, 0, v29, s[92:93]
	s_sub_i32 s97, s6, 0xa40
	v_cmp_gt_i32_e64 s[92:93], s97, v186
	v_cndmask_b32_e64 v27, 0, v27, s[94:95]
	s_sub_i32 s98, s6, 0xac0
	v_cmp_gt_i32_e64 s[94:95], s98, v186
	v_cndmask_b32_e64 v25, 0, v25, s[90:91]
	s_sub_i32 s96, s6, 0xb40
	v_cmp_gt_i32_e64 s[90:91], s96, v186
	v_cndmask_b32_e64 v23, 0, v23, s[92:93]
	s_sub_i32 s97, s6, 0xc40
	v_cmp_gt_i32_e64 s[92:93], s97, v186
	v_cndmask_b32_e64 v21, 0, v21, s[94:95]
	s_sub_i32 s98, s6, 0xcc0
	v_cmp_gt_i32_e64 s[94:95], s98, v186
	v_cndmask_b32_e64 v19, 0, v19, s[90:91]
	s_sub_i32 s96, s6, 0xd40
	v_cmp_gt_i32_e64 s[90:91], s96, v186
	v_cndmask_b32_e64 v15, 0, v15, s[92:93]
	s_sub_i32 s97, s6, 0xdc0
	v_cmp_gt_i32_e64 s[92:93], s97, v186
	v_cndmask_b32_e64 v13, 0, v13, s[94:95]
	s_sub_i32 s98, s6, 0xe40
	v_cmp_gt_i32_e64 s[94:95], s98, v186
	v_cndmask_b32_e64 v11, 0, v11, s[90:91]
	s_sub_i32 s96, s6, 0xec0
	v_cmp_gt_i32_e64 s[90:91], s96, v186
	v_cndmask_b32_e64 v9, 0, v9, s[92:93]
	s_sub_i32 s97, s6, 0xf40
	v_cmp_gt_i32_e64 s[92:93], s97, v186
	v_cndmask_b32_e64 v7, 0, v7, s[94:95]
	s_sub_i32 s98, s6, 0x80
	v_cmp_gt_i32_e64 s[94:95], s98, v186
	v_cndmask_b32_e64 v5, 0, v5, s[90:91]
	s_sub_i32 s96, s6, 0x100
	v_cmp_gt_i32_e64 s[90:91], s96, v186
	v_cndmask_b32_e64 v3, 0, v3, s[92:93]
	s_sub_i32 s97, s6, 0x180
	v_cmp_gt_i32_e64 s[92:93], s97, v186
	v_cndmask_b32_e64 v62, 0, v62, s[94:95]
	s_sub_i32 s98, s6, 0x200
	v_cmp_gt_i32_e64 s[94:95], s98, v186
	v_cndmask_b32_e64 v60, 0, v60, s[90:91]
	s_sub_i32 s96, s6, 0x280
	v_cmp_gt_i32_e64 s[90:91], s96, v186
	v_cndmask_b32_e64 v58, 0, v58, s[92:93]
	s_sub_i32 s97, s6, 0x300
	v_cmp_gt_i32_e64 s[92:93], s97, v186
	v_cndmask_b32_e64 v56, 0, v56, s[94:95]
	s_sub_i32 s98, s6, 0x380
	v_cmp_gt_i32_e64 s[94:95], s98, v186
	v_cndmask_b32_e64 v54, 0, v54, s[90:91]
	s_sub_i32 s96, s6, 0x400
	v_cmp_gt_i32_e64 s[90:91], s96, v186
	v_cndmask_b32_e64 v52, 0, v52, s[92:93]
	s_sub_i32 s97, s6, 0x480
	v_cmp_gt_i32_e64 s[92:93], s97, v186
	v_cndmask_b32_e64 v50, 0, v50, s[94:95]
	s_sub_i32 s98, s6, 0x500
	v_cmp_gt_i32_e64 s[94:95], s98, v186
	v_cndmask_b32_e64 v48, 0, v48, s[90:91]
	s_sub_i32 s96, s6, 0x580
	v_cmp_gt_i32_e64 s[90:91], s96, v186
	v_cndmask_b32_e64 v46, 0, v46, s[92:93]
	s_sub_i32 s97, s6, 0x600
	v_cmp_gt_i32_e64 s[92:93], s97, v186
	v_cndmask_b32_e64 v44, 0, v44, s[94:95]
	s_sub_i32 s98, s6, 0x680
	v_cmp_gt_i32_e64 s[94:95], s98, v186
	v_cndmask_b32_e64 v42, 0, v42, s[90:91]
	s_sub_i32 s96, s6, 0x700
	v_cmp_gt_i32_e64 s[90:91], s96, v186
	v_cndmask_b32_e64 v40, 0, v40, s[92:93]
	s_sub_i32 s97, s6, 0x780
	v_cmp_gt_i32_e64 s[92:93], s97, v186
	v_cndmask_b32_e64 v38, 0, v38, s[94:95]
	s_sub_i32 s98, s6, 0x800
	v_cmp_gt_i32_e64 s[94:95], s98, v186
	v_cndmask_b32_e64 v36, 0, v36, s[90:91]
	s_sub_i32 s96, s6, 0x880
	v_cmp_gt_i32_e64 s[90:91], s96, v186
	v_cndmask_b32_e64 v34, 0, v34, s[92:93]
	s_sub_i32 s97, s6, 0x900
	v_cmp_gt_i32_e64 s[92:93], s97, v186
	v_cndmask_b32_e64 v32, 0, v32, s[94:95]
	s_sub_i32 s98, s6, 0x980
	v_cmp_gt_i32_e64 s[94:95], s98, v186
	v_cndmask_b32_e64 v30, 0, v30, s[90:91]
	s_sub_i32 s96, s6, 0xa00
	v_cmp_gt_i32_e64 s[90:91], s96, v186
	v_cndmask_b32_e64 v28, 0, v28, s[92:93]
	s_sub_i32 s97, s6, 0xa80
	v_cmp_gt_i32_e64 s[92:93], s97, v186
	v_cndmask_b32_e64 v26, 0, v26, s[94:95]
	s_sub_i32 s98, s6, 0xb00
	v_cmp_gt_i32_e64 s[94:95], s98, v186
	v_cndmask_b32_e64 v24, 0, v24, s[90:91]
	s_sub_i32 s96, s6, 0xb80
	v_cmp_gt_i32_e64 s[90:91], s96, v186
	v_cndmask_b32_e64 v22, 0, v22, s[92:93]
	s_sub_i32 s97, s6, 0xc00
	v_cmp_gt_i32_e64 s[92:93], s97, v186
	v_cndmask_b32_e64 v20, 0, v20, s[94:95]
	s_sub_i32 s98, s6, 0xc80
	v_cmp_gt_i32_e64 s[94:95], s98, v186
	v_cndmask_b32_e64 v18, 0, v18, s[90:91]
	s_sub_i32 s96, s6, 0xd00
	v_cmp_gt_i32_e64 s[90:91], s96, v186
	v_cndmask_b32_e64 v16, 0, v16, s[92:93]
	s_sub_i32 s97, s6, 0xd80
	v_cmp_gt_i32_e64 s[92:93], s97, v186
	v_cndmask_b32_e64 v14, 0, v14, s[94:95]
	s_sub_i32 s98, s6, 0xe00
	v_cmp_gt_i32_e64 s[94:95], s98, v186
	v_cndmask_b32_e64 v12, 0, v12, s[90:91]
	s_sub_i32 s96, s6, 0xe80
	v_cmp_gt_i32_e64 s[90:91], s96, v186
	v_cndmask_b32_e64 v10, 0, v10, s[92:93]
	s_sub_i32 s97, s6, 0xf00
	v_cmp_gt_i32_e64 s[92:93], s97, v186
	v_cndmask_b32_e64 v8, 0, v8, s[94:95]
	v_cndmask_b32_e64 v6, 0, v6, s[90:91]
	v_cndmask_b32_e64 v4, 0, v4, s[92:93]
	s_add_i32 s6, s12, 63
	s_ashr_i32 s10, s6, 6
	s_cmpk_gt_i32 s12, 0x400
	s_cbranch_scc0 .LBB0_1712
